# v144 plus selection phase-1 DPP suffix scan, count-based in-lane scan, and pool tiles by finishing rank
# speedup vs baseline: 1.0057x; 1.0057x over previous
.LBB0_799:
	s_sub_i32 s98, s36, 0x804
	s_waitcnt vmcnt(0)
	s_add_u32 s0, s18, 0xfca8000
	s_addc_u32 s1, s19, 0
	v_readlane_b32 s4, v250, 30
	s_add_u32 s36, s18, 0x24128000
	v_readlane_b32 s5, v250, 31
	s_addc_u32 s37, s19, 0
	s_lshl_b64 s[38:39], s[4:5], 12
	s_mov_b64 s[40:41], s[18:19]
	v_readlane_b32 s4, v252, 19
	v_readlane_b32 s8, v252, 23
	v_readlane_b32 s9, v252, 24
	s_add_u32 s38, s8, s38
	v_readlane_b32 s10, v252, 25
	v_readlane_b32 s11, v252, 26
	s_addc_u32 s39, s9, s39
	s_mov_b32 s4, s98
	s_mov_b64 s[10:11], s[40:41]
	s_cmpk_gt_i32 s4, 0x7f
	v_readlane_b32 s5, v252, 20
	v_readlane_b32 s6, v252, 21
	v_readlane_b32 s7, v252, 22
	v_readlane_b32 s12, v252, 27
	v_readlane_b32 s13, v252, 28
	v_readlane_b32 s14, v252, 29
	v_readlane_b32 s15, v252, 30
	v_readlane_b32 s16, v252, 31
	v_readlane_b32 s17, v252, 32
	v_readlane_b32 s18, v252, 33
	v_readlane_b32 s19, v252, 34
	s_cbranch_scc1 .LBB0_806
	s_add_u32 s48, s10, 0xec28000
	s_mov_b32 s58, s98
	s_addc_u32 s49, s11, 0
	s_lshl_b32 s40, s58, 8
	v_readlane_b32 s4, v250, 32
	s_or_b32 s50, s40, 0xb0
	s_lshl_b32 s51, s4, 8
	s_branch .LBB0_802
